# group barriers skip the L2 write-back when all workgroups of the group are verified (HW_REG_XCC_ID via atomic max words) to sit on one XCD; falls back to the full release otherwise
# speedup vs baseline: 1.0387x; 1.0181x over previous
; __global__ void __launch_bounds__(NTHR, 2) fwd_kernel(Params p) {
;     extern __shared__ __attribute__((aligned(16))) unsigned char smem[];
;     cg::grid_group grid = cg::this_grid();
;     if (blockIdx.x == 0 && threadIdx.x < 9) p.bar[64 * threadIdx.x] = 0u;
;     phase0(p, smem);
_Z10fwd_kernel6Params:
	s_load_dwordx16 s[60:75], s[0:1], 0x100
	s_load_dwordx16 s[4:19], s[0:1], 0x140
	s_mov_b32 s94, s2
	s_add_u32 s2, s0, 0x198
	s_load_dwordx4 s[28:31], s[0:1], 0x180
	s_load_dword s92, s[0:1], 0x198
	s_addc_u32 s3, s1, 0
	s_waitcnt lgkmcnt(0)
	v_writelane_b32 v253, s4, 0
	s_cmp_eq_u32 s94, 0
	v_and_b32_e32 v234, 0x3ff, v0
	v_writelane_b32 v253, s5, 1
	v_writelane_b32 v253, s6, 2
	v_writelane_b32 v253, s7, 3
	v_writelane_b32 v253, s8, 4
	v_writelane_b32 v253, s9, 5
	v_writelane_b32 v253, s10, 6
	v_writelane_b32 v253, s11, 7
	v_writelane_b32 v253, s12, 8
	v_writelane_b32 v253, s13, 9
	v_writelane_b32 v253, s14, 10
	v_writelane_b32 v253, s15, 11
	v_writelane_b32 v253, s16, 12
	v_writelane_b32 v253, s17, 13
	v_writelane_b32 v253, s18, 14
	v_writelane_b32 v253, s19, 15
	s_cselect_b64 s[4:5], -1, 0
	v_cmp_gt_u32_e32 vcc, 9, v234
	s_and_b64 s[6:7], s[4:5], vcc
	s_and_saveexec_b64 s[4:5], s[6:7]
	s_cbranch_execz .LBB0_2
	v_lshlrev_b32_e32 v1, 8, v234
	v_mov_b32_e32 v2, 0
	global_store_dword v1, v2, s[30:31]
	global_store_dword v1, v2, s[30:31] offset:4
	global_store_dword v1, v2, s[30:31] offset:8

; __device__ __forceinline__ void grid_barrier(unsigned* ctr, unsigned target) {
;     asm volatile("s_waitcnt vmcnt(0)" ::: "memory");
;     __syncthreads();
;     if (threadIdx.x == 0) {
;         __builtin_amdgcn_fence(__ATOMIC_RELEASE, "agent");
;         asm volatile("s_waitcnt vmcnt(0)" ::: "memory");
;         __hip_atomic_fetch_add(ctr, 1u, __ATOMIC_RELAXED, __HIP_MEMORY_SCOPE_AGENT);
;         while (__hip_atomic_load(ctr, __ATOMIC_RELAXED, __HIP_MEMORY_SCOPE_AGENT) < target) __builtin_amdgcn_s_sleep(1);
;         __builtin_amdgcn_fence(__ATOMIC_ACQUIRE, "agent");
;         asm volatile("s_waitcnt vmcnt(0)" ::: "memory");
;     }
;     __syncthreads();
; }
; __device__ __forceinline__ void group_barrier(unsigned* bar, unsigned target) {
;     grid_barrier(bar + 64 * (1 + (blockIdx.x & 7)), target);
; }
.LBB0_108:
	s_or_b64 exec, exec, s[2:3]
	s_lshl_b32 s0, s94, 8
	s_lshr_b32 s8, s92, 3
	s_and_b32 s0, s0, 0x700
	s_add_u32 s0, s30, s0
	s_addc_u32 s1, s31, 0
	s_waitcnt vmcnt(0)
	v_writelane_b32 v254, s0, 0
	s_barrier
	s_nop 0
	v_writelane_b32 v254, s1, 1
	v_cmp_eq_u32_e64 s[2:3], 0, v234
	s_mov_b64 s[0:1], exec
	s_nop 0
	v_writelane_b32 v254, s2, 2
	s_nop 1
	v_writelane_b32 v254, s3, 3
	s_and_b64 s[2:3], s[0:1], s[2:3]
	s_mov_b64 exec, s[2:3]
	s_cbranch_execz .LBB0_115
	s_mov_b64 s[2:3], exec
	s_getreg_b32 s98, hwreg(HW_REG_XCC_ID, 0, 4)
	v_readlane_b32 s10, v254, 0
	v_readlane_b32 s11, v254, 1
	s_sub_i32 s99, 7, s98
	v_mov_b32_e32 v0, 0
	v_mov_b32_e32 v1, s98
	v_mov_b32_e32 v2, s99
	s_nop 4
	global_atomic_umax v0, v1, s[10:11] offset:260
	global_atomic_umax v0, v2, s[10:11] offset:264
	buffer_wbl2 sc1
	s_waitcnt vmcnt(0)
	s_waitcnt vmcnt(0)
	v_mbcnt_lo_u32_b32 v0, s2, 0
	v_mbcnt_hi_u32_b32 v0, s3, v0
	v_cmp_eq_u32_e32 vcc, 0, v0
	s_and_saveexec_b64 s[4:5], vcc
	v_readlane_b32 s10, v254, 0
	v_readlane_b32 s11, v254, 1
	s_cbranch_execz .LBB0_111
	s_bcnt1_i32_b64 s2, s[2:3]
	v_mov_b32_e32 v0, 0
	v_mov_b32_e32 v1, s2
	s_nop 0
	global_atomic_add v0, v1, s[10:11] offset:256

; __device__ __forceinline__ void grid_barrier(unsigned* ctr, unsigned target) {
;     ...
;         while (__hip_atomic_load(ctr, __ATOMIC_RELAXED, __HIP_MEMORY_SCOPE_AGENT) < target) __builtin_amdgcn_s_sleep(1);
;         __builtin_amdgcn_fence(__ATOMIC_ACQUIRE, "agent");
;         asm volatile("s_waitcnt vmcnt(0)" ::: "memory");
;     }
.LBB0_114:
	buffer_inv sc1
	s_waitcnt vmcnt(0)
	global_load_dword v1, v0, s[10:11] offset:260 sc1
	global_load_dword v2, v0, s[10:11] offset:264 sc1
	s_waitcnt vmcnt(0)
	v_add_u32_e32 v1, v1, v2
	s_nop 0
	v_readfirstlane_b32 s98, v1

; __device__ __forceinline__ void grid_barrier(unsigned* ctr, unsigned target) {
;     asm volatile("s_waitcnt vmcnt(0)" ::: "memory");
;     __syncthreads();
;     if (threadIdx.x == 0) {
;         __builtin_amdgcn_fence(__ATOMIC_RELEASE, "agent");
;         asm volatile("s_waitcnt vmcnt(0)" ::: "memory");
;         __hip_atomic_fetch_add(ctr, 1u, __ATOMIC_RELAXED, __HIP_MEMORY_SCOPE_AGENT);
.LBB0_246:
	v_readlane_b32 s4, v254, 4
	s_waitcnt vmcnt(0)
	s_add_i32 s4, s44, s4
	s_waitcnt vmcnt(0)
	v_writelane_b32 v254, s4, 62
	s_barrier
	s_mov_b64 s[4:5], exec
	v_readlane_b32 s6, v254, 2
	v_readlane_b32 s7, v254, 3
	s_and_b64 s[6:7], s[4:5], s[6:7]
	s_mov_b64 exec, s[6:7]
	s_cbranch_execz .LBB0_252
	s_mov_b64 s[6:7], exec
	s_cmp_eq_u32 s98, 7
	s_cbranch_scc1 .Lwb_skip_2
	buffer_wbl2 sc1
.Lwb_skip_2:
	s_waitcnt vmcnt(0)
	v_mbcnt_lo_u32_b32 v0, s6, 0
	v_mbcnt_hi_u32_b32 v0, s7, v0
	v_cmp_eq_u32_e32 vcc, 0, v0
	s_and_saveexec_b64 s[8:9], vcc
	v_readlane_b32 s12, v254, 0
	v_readlane_b32 s13, v254, 1
	s_cbranch_execz .LBB0_249
	s_bcnt1_i32_b64 s6, s[6:7]
	v_mov_b32_e32 v0, s6
	s_nop 1
	global_atomic_add v1, v0, s[12:13] offset:256

; __device__ __forceinline__ void grid_barrier(unsigned* ctr, unsigned target) {
;     asm volatile("s_waitcnt vmcnt(0)" ::: "memory");
;     __syncthreads();
;     if (threadIdx.x == 0) {
;         __builtin_amdgcn_fence(__ATOMIC_RELEASE, "agent");
;         asm volatile("s_waitcnt vmcnt(0)" ::: "memory");
;         __hip_atomic_fetch_add(ctr, 1u, __ATOMIC_RELAXED, __HIP_MEMORY_SCOPE_AGENT);
.LBB0_762:
	s_waitcnt vmcnt(0)
	v_readlane_b32 s4, v254, 4
	s_add_i32 s44, s33, s4
	s_barrier
	s_mov_b64 s[4:5], exec
	v_readlane_b32 s6, v254, 2
	v_readlane_b32 s7, v254, 3
	s_and_b64 s[6:7], s[4:5], s[6:7]
	s_mov_b64 exec, s[6:7]
	s_cbranch_execz .LBB0_768
	s_mov_b64 s[6:7], exec
	s_cmp_eq_u32 s98, 7
	s_cbranch_scc1 .Lwb_skip_1
	buffer_wbl2 sc1
.Lwb_skip_1:
	s_waitcnt vmcnt(0)
	s_waitcnt vmcnt(0)
	v_mbcnt_lo_u32_b32 v0, s6, 0
	v_mbcnt_hi_u32_b32 v0, s7, v0
	v_cmp_eq_u32_e32 vcc, 0, v0
	s_and_saveexec_b64 s[8:9], vcc
	v_readlane_b32 s12, v254, 0
	v_readlane_b32 s13, v254, 1
	s_cbranch_execz .LBB0_765
	s_bcnt1_i32_b64 s6, s[6:7]
	v_mov_b32_e32 v0, s6
	s_nop 1
	global_atomic_add v1, v0, s[12:13] offset:256

; __device__ __forceinline__ void grid_barrier(unsigned* ctr, unsigned target) {
;     asm volatile("s_waitcnt vmcnt(0)" ::: "memory");
;     __syncthreads();
;     if (threadIdx.x == 0) {
;         __builtin_amdgcn_fence(__ATOMIC_RELEASE, "agent");
;         asm volatile("s_waitcnt vmcnt(0)" ::: "memory");
;         __hip_atomic_fetch_add(ctr, 1u, __ATOMIC_RELAXED, __HIP_MEMORY_SCOPE_AGENT);
.LBB0_799:
	s_waitcnt vmcnt(0)
	v_readlane_b32 s4, v254, 4
	s_add_i32 s44, s44, s4
	s_barrier
	s_mov_b64 s[4:5], exec
	v_readlane_b32 s10, v254, 2
	v_readlane_b32 s11, v254, 3
	s_and_b64 s[10:11], s[4:5], s[10:11]
	s_mov_b64 exec, s[10:11]
	s_cbranch_execz .LBB0_805
	s_mov_b64 s[10:11], exec
	s_cmp_eq_u32 s98, 7
	s_cbranch_scc1 .Lwb_skip_0
	buffer_wbl2 sc1
.Lwb_skip_0:
	s_waitcnt vmcnt(0)
	s_waitcnt vmcnt(0)
	v_mbcnt_lo_u32_b32 v0, s10, 0
	v_mbcnt_hi_u32_b32 v0, s11, v0
	v_cmp_eq_u32_e32 vcc, 0, v0
	s_and_saveexec_b64 s[12:13], vcc
	v_readlane_b32 s16, v254, 0
	v_readlane_b32 s17, v254, 1
	s_cbranch_execz .LBB0_802
	s_bcnt1_i32_b64 s10, s[10:11]
	v_mov_b32_e32 v0, s10
	s_nop 1
	global_atomic_add v1, v0, s[16:17] offset:256

; __global__ void __launch_bounds__(NTHR, 2) fwd_kernel(Params p) {
	.amdhsa_kernel _Z10fwd_kernel6Params
		.amdhsa_group_segment_fixed_size 0
		.amdhsa_private_segment_fixed_size 0
		.amdhsa_kernarg_size 664
		.amdhsa_user_sgpr_count 2
		.amdhsa_user_sgpr_dispatch_ptr 0
		.amdhsa_user_sgpr_queue_ptr 0
		.amdhsa_user_sgpr_kernarg_segment_ptr 1
		.amdhsa_user_sgpr_dispatch_id 0
		.amdhsa_user_sgpr_kernarg_preload_length 0
		.amdhsa_user_sgpr_kernarg_preload_offset 0
		.amdhsa_user_sgpr_private_segment_size 0
		.amdhsa_uses_dynamic_stack 0
		.amdhsa_enable_private_segment 0
		.amdhsa_system_sgpr_workgroup_id_x 1
		.amdhsa_system_sgpr_workgroup_id_y 0
		.amdhsa_system_sgpr_workgroup_id_z 0
		.amdhsa_system_sgpr_workgroup_info 0
		.amdhsa_system_vgpr_workitem_id 2
		.amdhsa_next_free_vgpr 256
		.amdhsa_next_free_sgpr 100
		.amdhsa_accum_offset 256
		.amdhsa_reserve_vcc 1
		.amdhsa_float_round_mode_32 0
		.amdhsa_float_round_mode_16_64 0
		.amdhsa_float_denorm_mode_32 3
		.amdhsa_float_denorm_mode_16_64 3
		.amdhsa_dx10_clamp 1
		.amdhsa_ieee_mode 1
		.amdhsa_fp16_overflow 0
		.amdhsa_tg_split 0
		.amdhsa_exception_fp_ieee_invalid_op 0
		.amdhsa_exception_fp_denorm_src 0
		.amdhsa_exception_fp_ieee_div_zero 0
		.amdhsa_exception_fp_ieee_overflow 0
		.amdhsa_exception_fp_ieee_underflow 0
		.amdhsa_exception_fp_ieee_inexact 0
		.amdhsa_exception_int_div_zero 0
	.end_amdhsa_kernel

; __global__ void __launch_bounds__(NTHR, 2) fwd_kernel(Params p) {
.Lfunc_end0:
	.size	_Z10fwd_kernel6Params, .Lfunc_end0-_Z10fwd_kernel6Params
	.set _Z10fwd_kernel6Params.num_vgpr, 256
	.set _Z10fwd_kernel6Params.num_agpr, 0
	.set _Z10fwd_kernel6Params.numbered_sgpr, 100
	.set _Z10fwd_kernel6Params.num_named_barrier, 0
	.set _Z10fwd_kernel6Params.private_seg_size, 0
	.set _Z10fwd_kernel6Params.uses_vcc, 1
	.set _Z10fwd_kernel6Params.uses_flat_scratch, 0
	.set _Z10fwd_kernel6Params.has_dyn_sized_stack, 0
	.set _Z10fwd_kernel6Params.has_recursion, 0
	.set _Z10fwd_kernel6Params.has_indirect_call, 0

; __global__ void __launch_bounds__(NTHR, 2) fwd_kernel(Params p) {
amdhsa.kernels:
  - .agpr_count:     0
    .args:
      - .offset:         0
        .size:           408
        .value_kind:     by_value
      - .offset:         408
        .size:           4
        .value_kind:     hidden_block_count_x
      - .offset:         412
        .size:           4
        .value_kind:     hidden_block_count_y
      - .offset:         416
        .size:           4
        .value_kind:     hidden_block_count_z
      - .offset:         420
        .size:           2
        .value_kind:     hidden_group_size_x
      - .offset:         422
        .size:           2
        .value_kind:     hidden_group_size_y
      - .offset:         424
        .size:           2
        .value_kind:     hidden_group_size_z
      - .offset:         426
        .size:           2
        .value_kind:     hidden_remainder_x
      - .offset:         428
        .size:           2
        .value_kind:     hidden_remainder_y
      - .offset:         430
        .size:           2
        .value_kind:     hidden_remainder_z
      - .offset:         448
        .size:           8
        .value_kind:     hidden_global_offset_x
      - .offset:         456
        .size:           8
        .value_kind:     hidden_global_offset_y
      - .offset:         464
        .size:           8
        .value_kind:     hidden_global_offset_z
      - .offset:         472
        .size:           2
        .value_kind:     hidden_grid_dims
      - .offset:         496
        .size:           8
        .value_kind:     hidden_multigrid_sync_arg
      - .offset:         528
        .size:           4
        .value_kind:     hidden_dynamic_lds_size
    .group_segment_fixed_size: 0
    .kernarg_segment_align: 8
    .kernarg_segment_size: 664
    .language:       OpenCL C
    .language_version:
      - 2
      - 0
    .max_flat_workgroup_size: 512
    .name:           _Z10fwd_kernel6Params
    .private_segment_fixed_size: 0
    .sgpr_count:     106
    .sgpr_spill_count: 151
    .symbol:         _Z10fwd_kernel6Params.kd
    .uniform_work_group_size: 1
    .uses_dynamic_stack: false
    .vgpr_count:     256
    .vgpr_spill_count: 0
    .wavefront_size: 64
